# norm-phase XN stores (8 B) write-through sc1 (on top of v18)
# baseline (speedup 1.0000x reference)
.LBB0_191:
	s_waitcnt vmcnt(3)
	v_mul_f32_e32 v0, v31, v31
	s_waitcnt vmcnt(2)
	v_mul_f32_e32 v42, v27, v27
	v_fmac_f32_e32 v0, v30, v30
	v_fmac_f32_e32 v42, v26, v26
	v_fmac_f32_e32 v0, v32, v32
	v_fmac_f32_e32 v42, v28, v28
	v_fmac_f32_e32 v0, v33, v33
	v_fmac_f32_e32 v42, v29, v29
	s_waitcnt vmcnt(0)
	v_pk_mul_f32 v[46:47], v[18:19], v[18:19]
	v_pk_mul_f32 v[58:59], v[22:23], v[22:23]
	v_add_f32_e32 v0, v0, v42
	v_pk_mul_f32 v[42:43], v[20:21], v[20:21]
	v_pk_mul_f32 v[44:45], v[24:25], v[24:25]
	v_mov_b32_e32 v60, v46
	v_mov_b32_e32 v61, v58
	v_mov_b32_e32 v58, v47
	v_pk_add_f32 v[46:47], v[60:61], v[58:59]
	v_mov_b32_e32 v58, v42
	v_mov_b32_e32 v59, v44
	v_pk_add_f32 v[46:47], v[58:59], v[46:47]
	v_mov_b32_e32 v44, v43
	v_pk_add_f32 v[42:43], v[44:45], v[46:47]
	s_cmpk_lt_u32 s2, 0x4000
	v_add_f32_e32 v0, v43, v0
	v_add_f32_e32 v0, v42, v0
	ds_bpermute_b32 v42, v35, v0
	s_movk_i32 s0, 0x4800
	s_cselect_b32 s0, 0x2400, s0
	s_cmpk_gt_i32 s2, 0x1fff
	s_cselect_b32 s0, s0, 0
	s_waitcnt lgkmcnt(0)
	v_add_f32_e32 v0, v0, v42
	ds_bpermute_b32 v42, v48, v0
	s_lshl_b32 s0, s0, 2
	v_readlane_b32 s1, v254, 45
	s_add_u32 s0, s1, s0
	v_readlane_b32 s1, v254, 47
	s_waitcnt lgkmcnt(0)
	v_add_f32_e32 v0, v0, v42
	ds_bpermute_b32 v42, v49, v0
	s_addc_u32 s1, s1, 0
	s_add_u32 s4, s0, 0x3000
	s_addc_u32 s5, s1, 0
	s_add_u32 s6, s0, 0x4000
	s_waitcnt lgkmcnt(0)
	v_add_f32_e32 v0, v0, v42
	ds_bpermute_b32 v42, v50, v0
	s_addc_u32 s7, s1, 0
	s_waitcnt lgkmcnt(0)
	v_add_f32_e32 v0, v0, v42
	ds_bpermute_b32 v42, v51, v0
	s_waitcnt lgkmcnt(0)
	v_add_f32_e32 v0, v0, v42
	ds_bpermute_b32 v42, v52, v0
	s_waitcnt lgkmcnt(0)
	v_add_f32_e32 v0, v0, v42
	v_fmamk_f32 v0, v0, 0x3a800000, v199
	v_cmp_gt_f32_e32 vcc, s21, v0
	v_mul_f32_e32 v42, 0x4f800000, v0
	s_nop 0
	v_cndmask_b32_e32 v0, v0, v42, vcc
	v_sqrt_f32_e32 v42, v0
	s_nop 0
	v_add_u32_e32 v43, -1, v42
	v_fma_f32 v44, -v43, v42, v0
	v_cmp_ge_f32_e64 s[38:39], 0, v44
	v_add_u32_e32 v44, 1, v42
	s_nop 0
	v_cndmask_b32_e64 v43, v42, v43, s[38:39]
	v_fma_f32 v42, -v44, v42, v0
	v_cmp_lt_f32_e64 s[38:39], 0, v42
	s_nop 1
	v_cndmask_b32_e64 v42, v43, v44, s[38:39]
	v_mul_f32_e32 v43, 0x37800000, v42
	v_cndmask_b32_e32 v42, v42, v43, vcc
	v_cmp_class_f32_e32 vcc, v0, v200
	s_nop 1
	v_cndmask_b32_e32 v0, v42, v0, vcc
	v_div_scale_f32 v42, s[0:1], v0, v0, 1.0
	v_rcp_f32_e32 v43, v42
	v_readlane_b32 s0, v249, 52
	v_readlane_b32 s1, v249, 53
	s_add_u32 s2, s2, s0
	v_fma_f32 v44, -v42, v43, 1.0
	v_fmac_f32_e32 v43, v44, v43
	v_div_scale_f32 v44, vcc, 1.0, v0, 1.0
	v_mul_f32_e32 v45, v44, v43
	v_fma_f32 v46, -v42, v45, v44
	v_fmac_f32_e32 v45, v46, v43
	v_fma_f32 v42, -v42, v45, v44
	v_div_fmas_f32 v42, v42, v43, v45
	v_div_fixup_f32 v0, v42, v0, 1.0
	global_load_dwordx4 v[42:45], v56, s[6:7]
	s_nop 0
	global_load_dwordx4 v[56:59], v56, s[4:5]
	v_pk_mul_f32 v[30:31], v[30:31], v[0:1] op_sel_hi:[1,0]
	v_pk_mul_f32 v[32:33], v[32:33], v[0:1] op_sel_hi:[1,0]
	v_pk_mul_f32 v[30:31], v[2:3], v[30:31]
	v_pk_mul_f32 v[32:33], v[4:5], v[32:33]
	v_pk_mul_f32 v[26:27], v[26:27], v[0:1] op_sel_hi:[1,0]
	v_pk_mul_f32 v[28:29], v[28:29], v[0:1] op_sel_hi:[1,0]
	v_pk_mul_f32 v[26:27], v[6:7], v[26:27]
	v_pk_mul_f32 v[28:29], v[8:9], v[28:29]
	v_pk_mul_f32 v[22:23], v[22:23], v[0:1] op_sel_hi:[1,0]
	v_pk_mul_f32 v[24:25], v[24:25], v[0:1] op_sel_hi:[1,0]
	v_pk_mul_f32 v[22:23], v[10:11], v[22:23]
	v_pk_mul_f32 v[24:25], v[12:13], v[24:25]
	v_pk_mul_f32 v[18:19], v[18:19], v[0:1] op_sel_hi:[1,0]
	v_pk_mul_f32 v[20:21], v[20:21], v[0:1] op_sel_hi:[1,0]
	v_pk_mul_f32 v[18:19], v[18:19], v[14:15]
	v_pk_mul_f32 v[20:21], v[20:21], v[16:17]
	s_addc_u32 s3, s3, s1
	v_readlane_b32 s0, v253, 22
	v_readlane_b32 s1, v253, 23
	s_cmpk_gt_i32 s2, 0x41ff
	s_waitcnt vmcnt(1)
	v_pk_add_f32 v[42:43], v[42:43], 1.0 op_sel_hi:[1,0]
	s_waitcnt vmcnt(0)
	v_pk_fma_f32 v[30:31], v[42:43], v[30:31], v[56:57]
	v_pk_add_f32 v[42:43], v[44:45], 1.0 op_sel_hi:[1,0]
	v_cvt_pk_bf16_f32 v30, v30, v31
	v_pk_fma_f32 v[32:33], v[42:43], v[32:33], v[58:59]
	s_nop 0
	v_cvt_pk_bf16_f32 v31, v32, v33
	global_store_dwordx2 v[40:41], v[30:31], off sc1
	global_load_dwordx4 v[30:33], v53, s[6:7]
	s_nop 0
	global_load_dwordx4 v[42:45], v53, s[4:5]
	s_waitcnt vmcnt(1)
	v_pk_add_f32 v[30:31], v[30:31], 1.0 op_sel_hi:[1,0]
	s_waitcnt vmcnt(0)
	v_pk_fma_f32 v[26:27], v[30:31], v[26:27], v[42:43]
	v_pk_add_f32 v[30:31], v[32:33], 1.0 op_sel_hi:[1,0]
	v_cvt_pk_bf16_f32 v26, v26, v27
	v_pk_fma_f32 v[28:29], v[30:31], v[28:29], v[44:45]
	s_nop 0
	v_cvt_pk_bf16_f32 v27, v28, v29
	global_store_dwordx2 v[40:41], v[26:27], off offset:512 sc1
	global_load_dwordx4 v[26:29], v54, s[6:7]
	s_nop 0
	global_load_dwordx4 v[30:33], v54, s[4:5]
	s_waitcnt vmcnt(1)
	v_pk_add_f32 v[26:27], v[26:27], 1.0 op_sel_hi:[1,0]
	s_waitcnt vmcnt(0)
	v_pk_fma_f32 v[22:23], v[22:23], v[26:27], v[30:31]
	v_pk_add_f32 v[26:27], v[28:29], 1.0 op_sel_hi:[1,0]
	v_cvt_pk_bf16_f32 v22, v22, v23
	v_pk_fma_f32 v[24:25], v[24:25], v[26:27], v[32:33]
	s_nop 0
	v_cvt_pk_bf16_f32 v23, v24, v25
	global_store_dwordx2 v[40:41], v[22:23], off offset:1024 sc1
	global_load_dwordx4 v[26:29], v55, s[6:7]
	s_nop 0
	global_load_dwordx4 v[22:25], v55, s[4:5]
	s_waitcnt vmcnt(1)
	v_pk_add_f32 v[26:27], v[26:27], 1.0 op_sel_hi:[1,0]
	s_waitcnt vmcnt(0)
	v_pk_fma_f32 v[18:19], v[18:19], v[26:27], v[22:23]
	v_pk_add_f32 v[22:23], v[28:29], 1.0 op_sel_hi:[1,0]
	v_cvt_pk_bf16_f32 v18, v18, v19
	v_pk_fma_f32 v[20:21], v[20:21], v[22:23], v[24:25]
	s_nop 0
	v_cvt_pk_bf16_f32 v19, v20, v21
	global_store_dwordx2 v[40:41], v[18:19], off offset:1536 sc1
	v_lshl_add_u64 v[40:41], v[40:41], 0, s[0:1]
	s_cbranch_scc1 .LBB0_194

.LBB0_1101:
	s_waitcnt vmcnt(3)
	v_mul_f32_e32 v0, v31, v31
	s_waitcnt vmcnt(2)
	v_mul_f32_e32 v40, v27, v27
	v_fmac_f32_e32 v0, v30, v30
	v_fmac_f32_e32 v40, v26, v26
	v_fmac_f32_e32 v0, v32, v32
	v_fmac_f32_e32 v40, v28, v28
	v_fmac_f32_e32 v0, v33, v33
	v_fmac_f32_e32 v40, v29, v29
	s_waitcnt vmcnt(0)
	v_pk_mul_f32 v[54:55], v[18:19], v[18:19]
	v_pk_mul_f32 v[56:57], v[22:23], v[22:23]
	v_add_f32_e32 v0, v0, v40
	v_pk_mul_f32 v[40:41], v[20:21], v[20:21]
	v_pk_mul_f32 v[52:53], v[24:25], v[24:25]
	v_mov_b32_e32 v58, v54
	v_mov_b32_e32 v59, v56
	v_mov_b32_e32 v56, v55
	v_pk_add_f32 v[54:55], v[58:59], v[56:57]
	v_mov_b32_e32 v56, v40
	v_mov_b32_e32 v57, v52
	v_pk_add_f32 v[54:55], v[56:57], v[54:55]
	v_mov_b32_e32 v52, v41
	v_pk_add_f32 v[40:41], v[52:53], v[54:55]
	s_cmpk_lt_u32 s6, 0x4000
	v_add_f32_e32 v0, v41, v0
	v_add_f32_e32 v0, v40, v0
	ds_bpermute_b32 v40, v42, v0
	s_movk_i32 s5, 0x4800
	s_cselect_b32 s5, 0x2400, s5
	s_cmpk_gt_i32 s6, 0x1fff
	s_cselect_b32 s5, s5, 0
	s_waitcnt lgkmcnt(0)
	v_add_f32_e32 v0, v0, v40
	ds_bpermute_b32 v40, v43, v0
	s_lshl_b32 s5, s5, 2
	s_add_u32 s8, s0, s5
	s_addc_u32 s9, s1, 0
	s_add_u32 s10, s8, 0x1000
	s_waitcnt lgkmcnt(0)
	v_add_f32_e32 v0, v0, v40
	ds_bpermute_b32 v40, v44, v0
	s_addc_u32 s11, s9, 0
	s_waitcnt lgkmcnt(0)
	v_add_f32_e32 v0, v0, v40
	ds_bpermute_b32 v40, v45, v0
	s_waitcnt lgkmcnt(0)
	v_add_f32_e32 v0, v0, v40
	ds_bpermute_b32 v40, v46, v0
	s_waitcnt lgkmcnt(0)
	v_add_f32_e32 v0, v0, v40
	ds_bpermute_b32 v40, v47, v0
	s_waitcnt lgkmcnt(0)
	v_add_f32_e32 v0, v0, v40
	v_fmamk_f32 v0, v0, 0x3a800000, v199
	v_cmp_gt_f32_e32 vcc, s21, v0
	v_mul_f32_e32 v40, 0x4f800000, v0
	s_nop 0
	v_cndmask_b32_e32 v0, v0, v40, vcc
	v_sqrt_f32_e32 v40, v0
	s_nop 0
	v_add_u32_e32 v41, -1, v40
	v_fma_f32 v52, -v41, v40, v0
	v_cmp_ge_f32_e64 s[38:39], 0, v52
	v_add_u32_e32 v52, 1, v40
	s_nop 0
	v_cndmask_b32_e64 v41, v40, v41, s[38:39]
	v_fma_f32 v40, -v52, v40, v0
	v_cmp_lt_f32_e64 s[38:39], 0, v40
	s_nop 1
	v_cndmask_b32_e64 v40, v41, v52, s[38:39]
	v_mul_f32_e32 v41, 0x37800000, v40
	v_cndmask_b32_e32 v40, v40, v41, vcc
	v_cmp_class_f32_e32 vcc, v0, v200
	s_nop 1
	v_cndmask_b32_e32 v0, v40, v0, vcc
	v_div_scale_f32 v40, s[16:17], v0, v0, 1.0
	v_rcp_f32_e32 v41, v40
	s_lshl_b64 s[16:17], s[6:7], 11
	v_fma_f32 v52, -v40, v41, 1.0
	v_fmac_f32_e32 v41, v52, v41
	v_div_scale_f32 v52, vcc, 1.0, v0, 1.0
	v_mul_f32_e32 v53, v52, v41
	v_fma_f32 v54, -v40, v53, v52
	v_fmac_f32_e32 v53, v54, v41
	v_fma_f32 v40, -v40, v53, v52
	v_div_fmas_f32 v40, v40, v41, v53
	global_load_dwordx4 v[52:55], v48, s[10:11]
	global_load_dwordx4 v[56:59], v48, s[8:9]
	v_div_fixup_f32 v0, v40, v0, 1.0
	v_pk_mul_f32 v[30:31], v[30:31], v[0:1] op_sel_hi:[1,0]
	v_pk_mul_f32 v[32:33], v[32:33], v[0:1] op_sel_hi:[1,0]
	v_pk_mul_f32 v[30:31], v[2:3], v[30:31]
	v_pk_mul_f32 v[32:33], v[4:5], v[32:33]
	v_pk_mul_f32 v[26:27], v[26:27], v[0:1] op_sel_hi:[1,0]
	v_pk_mul_f32 v[28:29], v[28:29], v[0:1] op_sel_hi:[1,0]
	v_pk_mul_f32 v[26:27], v[6:7], v[26:27]
	v_pk_mul_f32 v[28:29], v[8:9], v[28:29]
	v_pk_mul_f32 v[22:23], v[22:23], v[0:1] op_sel_hi:[1,0]
	v_pk_mul_f32 v[24:25], v[24:25], v[0:1] op_sel_hi:[1,0]
	v_pk_mul_f32 v[22:23], v[10:11], v[22:23]
	v_pk_mul_f32 v[24:25], v[12:13], v[24:25]
	v_pk_mul_f32 v[18:19], v[18:19], v[0:1] op_sel_hi:[1,0]
	v_pk_mul_f32 v[20:21], v[20:21], v[0:1] op_sel_hi:[1,0]
	v_pk_mul_f32 v[18:19], v[18:19], v[14:15]
	v_pk_mul_f32 v[20:21], v[20:21], v[16:17]
	s_waitcnt vmcnt(1)
	v_pk_add_f32 v[40:41], v[52:53], 1.0 op_sel_hi:[1,0]
	s_waitcnt vmcnt(0)
	v_pk_fma_f32 v[30:31], v[40:41], v[30:31], v[56:57]
	v_pk_add_f32 v[40:41], v[54:55], 1.0 op_sel_hi:[1,0]
	s_nop 0
	v_pk_fma_f32 v[32:33], v[40:41], v[32:33], v[58:59]
	v_cvt_pk_bf16_f32 v40, v30, v31
	v_cvt_pk_bf16_f32 v41, v32, v33
	v_lshl_add_u64 v[30:31], v[36:37], 0, s[16:17]
	global_store_dwordx2 v[30:31], v[40:41], off sc1
	global_load_dwordx4 v[52:55], v49, s[10:11]
	global_load_dwordx4 v[56:59], v48, s[8:9] offset:1024
	s_waitcnt vmcnt(1)
	v_pk_add_f32 v[32:33], v[52:53], 1.0 op_sel_hi:[1,0]
	s_waitcnt vmcnt(0)
	v_pk_fma_f32 v[26:27], v[32:33], v[26:27], v[56:57]
	v_pk_add_f32 v[32:33], v[54:55], 1.0 op_sel_hi:[1,0]
	v_cvt_pk_bf16_f32 v26, v26, v27
	v_pk_fma_f32 v[28:29], v[32:33], v[28:29], v[58:59]
	s_nop 0
	v_cvt_pk_bf16_f32 v27, v28, v29
	global_store_dwordx2 v[30:31], v[26:27], off offset:512 sc1
	global_load_dwordx4 v[26:29], v50, s[10:11]
	s_nop 0
	global_load_dwordx4 v[52:55], v48, s[8:9] offset:2048
	s_waitcnt vmcnt(1)
	v_pk_add_f32 v[26:27], v[26:27], 1.0 op_sel_hi:[1,0]
	s_waitcnt vmcnt(0)
	v_pk_fma_f32 v[22:23], v[22:23], v[26:27], v[52:53]
	v_pk_add_f32 v[26:27], v[28:29], 1.0 op_sel_hi:[1,0]
	v_cvt_pk_bf16_f32 v22, v22, v23
	v_pk_fma_f32 v[24:25], v[24:25], v[26:27], v[54:55]
	s_nop 0
	v_cvt_pk_bf16_f32 v23, v24, v25
	global_store_dwordx2 v[30:31], v[22:23], off offset:1024 sc1
	global_load_dwordx4 v[26:29], v51, s[10:11]
	s_nop 0
	global_load_dwordx4 v[22:25], v48, s[8:9] offset:3072
	v_readlane_b32 s8, v249, 52
	s_add_i32 s6, s6, s8
	s_add_i32 s4, s4, s8
	s_cmp_ge_i32 s6, s12
	v_readlane_b32 s9, v249, 53
	s_waitcnt vmcnt(1)
	v_pk_add_f32 v[26:27], v[26:27], 1.0 op_sel_hi:[1,0]
	s_waitcnt vmcnt(0)
	v_pk_fma_f32 v[18:19], v[18:19], v[26:27], v[22:23]
	v_pk_add_f32 v[22:23], v[28:29], 1.0 op_sel_hi:[1,0]
	v_cvt_pk_bf16_f32 v18, v18, v19
	v_pk_fma_f32 v[20:21], v[20:21], v[22:23], v[24:25]
	s_nop 0
	v_cvt_pk_bf16_f32 v19, v20, v21
	global_store_dwordx2 v[30:31], v[18:19], off offset:1536 sc1
	s_cbranch_scc1 .LBB0_1106
